# v20: prologue weight transposes fetch the 32 per-k norm gains of an item with back-to-back loads and counted waits instead of load + vmcnt(0) per element
# speedup vs baseline: 1.0238x; 1.0020x over previous
; #define LAS __attribute__((address_space(3)))
; #define LDS_WAIT() asm volatile("s_waitcnt lgkmcnt(0)" ::: "memory")
; __device__ __forceinline__ void tr_load(float (&v)[32], const TrDesc& d, int lane) {
;     const float* p = d.W + (size_t)(d.k0 + (lane >> 5)) * d.N + d.n0 + (lane & 31);
; #pragma unroll
;     for (int i = 0; i < 32; ++i) v[i] = __builtin_nontemporal_load(p + (size_t)(2 * i) * d.N);
; }
; __device__ __forceinline__ void tr_store(const float (&v)[32], const TrDesc& d, LAS float* scr, int lane) {
; #pragma unroll
;     for (int i = 0; i < 32; ++i) { const int kk = 2 * i + (lane >> 5); float x = v[i]; if (d.gk) x *= d.gk[d.k0 + kk]; scr[kk * 33 + (lane & 31)] = x; }
;     LDS_WAIT();
.LBB0_564:
	s_cmp_eq_u64 s[14:15], 0
	s_cbranch_scc1 .Lgkp_skip
	v_add_u32_e32 v188, s16, v32
	v_ashrrev_i32_e32 v189, 31, v188
	v_lshl_add_u64 v[188:189], v[188:189], 2, s[14:15]
	global_load_dword v190, v[188:189], off
	global_load_dword v191, v[188:189], off offset:8
	global_load_dword v192, v[188:189], off offset:16
	global_load_dword v193, v[188:189], off offset:24
	global_load_dword v194, v[188:189], off offset:32
	global_load_dword v195, v[188:189], off offset:40
	global_load_dword v196, v[188:189], off offset:48
	global_load_dword v197, v[188:189], off offset:56
	global_load_dword v198, v[188:189], off offset:64
	global_load_dword v199, v[188:189], off offset:72
	global_load_dword v200, v[188:189], off offset:80
	global_load_dword v201, v[188:189], off offset:88
	global_load_dword v202, v[188:189], off offset:96
	global_load_dword v203, v[188:189], off offset:104
	global_load_dword v204, v[188:189], off offset:112
	global_load_dword v205, v[188:189], off offset:120
	global_load_dword v206, v[188:189], off offset:128
	global_load_dword v207, v[188:189], off offset:136
	global_load_dword v208, v[188:189], off offset:144
	global_load_dword v209, v[188:189], off offset:152
	global_load_dword v210, v[188:189], off offset:160
	global_load_dword v211, v[188:189], off offset:168
	global_load_dword v212, v[188:189], off offset:176
	global_load_dword v213, v[188:189], off offset:184
	global_load_dword v214, v[188:189], off offset:192
	global_load_dword v215, v[188:189], off offset:200
	global_load_dword v216, v[188:189], off offset:208
	global_load_dword v217, v[188:189], off offset:216
	global_load_dword v218, v[188:189], off offset:224
	global_load_dword v219, v[188:189], off offset:232
	global_load_dword v220, v[188:189], off offset:240
	global_load_dword v221, v[188:189], off offset:248
.Lgkp_skip:
	s_lshr_b32 s19, s84, 5
	v_cvt_f32_i32_e32 v35, s19
	s_sext_i32_i16 s21, s17
	v_cvt_f32_i32_e32 v75, s21
	s_ashr_i32 s21, s21, 30
	v_rcp_iflag_f32_e32 v76, v35
	s_or_b32 s21, s21, 1
	v_mul_f32_e32 v76, v75, v76
	v_trunc_f32_e32 v76, v76
	v_fma_f32 v75, -v76, v35, v75
	v_cvt_i32_f32_e32 v76, v76
	v_cmp_ge_f32_e64 s[24:25], |v75|, v35
	s_and_b64 s[24:25], s[24:25], exec
	s_cselect_b32 s21, s21, 0
	v_readfirstlane_b32 s24, v76
	s_add_i32 s21, s24, s21
	s_sext_i32_i16 s24, s21
	s_mul_i32 s21, s21, s19
	s_lshl_b32 s19, s24, 6
	s_sub_i32 s17, s17, s21
	s_sext_i32_i16 s17, s17
	v_or_b32_e32 v35, s19, v32
	s_lshl_b32 s74, s17, 5
	v_mul_hi_i32_i24_e32 v77, s84, v35
	v_mul_i32_i24_e32 v76, s84, v35
	v_lshl_add_u64 v[76:77], v[76:77], 2, s[6:7]
	s_ashr_i32 s75, s74, 31
	v_lshl_add_u64 v[76:77], s[74:75], 2, v[76:77]
	v_lshl_add_u64 v[76:77], v[76:77], 0, v[128:129]
	s_lshl_b64 s[6:7], s[84:85], 3
	v_lshl_add_u64 v[78:79], v[76:77], 0, s[6:7]
	v_lshl_add_u64 v[80:81], v[78:79], 0, s[6:7]
	v_lshl_add_u64 v[82:83], v[80:81], 0, s[6:7]
	v_lshl_add_u64 v[84:85], v[82:83], 0, s[6:7]
	v_lshl_add_u64 v[86:87], v[84:85], 0, s[6:7]
	v_lshl_add_u64 v[88:89], v[86:87], 0, s[6:7]
	v_lshl_add_u64 v[90:91], v[88:89], 0, s[6:7]
	global_load_dword v75, v[76:77], off nt
	s_nop 0
	global_load_dword v76, v[78:79], off nt
	global_load_dword v77, v[80:81], off nt
	s_nop 0
	global_load_dword v78, v[82:83], off nt
	global_load_dword v79, v[84:85], off nt
	global_load_dword v80, v[86:87], off nt
	global_load_dword v81, v[88:89], off nt
	s_nop 0
	global_load_dword v82, v[90:91], off nt
	v_lshl_add_u64 v[84:85], v[90:91], 0, s[6:7]
	global_load_dword v99, v[84:85], off nt
	v_lshl_add_u64 v[84:85], v[84:85], 0, s[6:7]
	global_load_dword v100, v[84:85], off nt
	v_lshl_add_u64 v[84:85], v[84:85], 0, s[6:7]
	global_load_dword v101, v[84:85], off nt
	v_lshl_add_u64 v[84:85], v[84:85], 0, s[6:7]
	global_load_dword v102, v[84:85], off nt
	v_lshl_add_u64 v[84:85], v[84:85], 0, s[6:7]
	global_load_dword v103, v[84:85], off nt
	v_lshl_add_u64 v[84:85], v[84:85], 0, s[6:7]
	global_load_dword v104, v[84:85], off nt
	v_lshl_add_u64 v[84:85], v[84:85], 0, s[6:7]
	global_load_dword v105, v[84:85], off nt
	v_lshl_add_u64 v[84:85], v[84:85], 0, s[6:7]
	global_load_dword v106, v[84:85], off nt
	v_lshl_add_u64 v[84:85], v[84:85], 0, s[6:7]
	v_lshl_add_u64 v[86:87], v[84:85], 0, s[6:7]
	global_load_dword v83, v[84:85], off nt
	s_cmp_lg_u64 s[14:15], 0
	global_load_dword v84, v[86:87], off nt
	v_lshl_add_u64 v[86:87], v[86:87], 0, s[6:7]
	v_lshl_add_u64 v[88:89], v[86:87], 0, s[6:7]
	global_load_dword v85, v[86:87], off nt
	s_cselect_b64 s[86:87], -1, 0
	global_load_dword v86, v[88:89], off nt
	v_lshl_add_u64 v[88:89], v[88:89], 0, s[6:7]
	v_lshl_add_u64 v[90:91], v[88:89], 0, s[6:7]
	global_load_dword v87, v[88:89], off nt
	s_cmp_eq_u64 s[14:15], 0
	global_load_dword v88, v[90:91], off nt
	v_lshl_add_u64 v[90:91], v[90:91], 0, s[6:7]
	v_lshl_add_u64 v[92:93], v[90:91], 0, s[6:7]
	global_load_dword v89, v[90:91], off nt
	s_nop 0
	global_load_dword v90, v[92:93], off nt
	v_lshl_add_u64 v[92:93], v[92:93], 0, s[6:7]
	v_lshl_add_u64 v[94:95], v[92:93], 0, s[6:7]
	global_load_dword v91, v[92:93], off nt
	s_nop 0
	global_load_dword v92, v[94:95], off nt
	v_lshl_add_u64 v[94:95], v[94:95], 0, s[6:7]
	v_lshl_add_u64 v[96:97], v[94:95], 0, s[6:7]
	global_load_dword v93, v[94:95], off nt
	s_nop 0
	global_load_dword v94, v[96:97], off nt
	v_lshl_add_u64 v[96:97], v[96:97], 0, s[6:7]
	v_lshl_add_u64 v[108:109], v[96:97], 0, s[6:7]
	global_load_dword v95, v[96:97], off nt
	s_nop 0
	global_load_dword v96, v[108:109], off nt
	v_lshl_add_u64 v[108:109], v[108:109], 0, s[6:7]
	global_load_dword v97, v[108:109], off nt
	v_lshl_add_u64 v[108:109], v[108:109], 0, s[6:7]
	global_load_dword v98, v[108:109], off nt
	s_cbranch_scc1 .LBB0_566
	v_add_u32_e32 v108, s16, v32
	v_ashrrev_i32_e32 v109, 31, v108
	v_lshl_add_u64 v[108:109], v[108:109], 2, s[14:15]
	s_waitcnt vmcnt(63)
	v_mul_f32_e32 v0, v0, v190
	s_nop 0
; __device__ __forceinline__ void tr_store(const float (&v)[32], const TrDesc& d, LAS float* scr, int lane) {
;     ...
;     for (int i = 0; i < 32; ++i) { const int kk = 2 * i + (lane >> 5); float x = v[i]; if (d.gk) x *= d.gk[d.k0 + kk]; scr[kk * 33 + (lane & 31)] = x; }
.LBB0_566:
	v_cndmask_b32_e64 v35, 0, 1, s[86:87]
	v_cmp_ne_u32_e64 s[6:7], 1, v35
	s_andn2_b64 vcc, exec, s[86:87]
	s_waitcnt vmcnt(62)
	ds_write_b32 v73, v0
	s_cbranch_vccnz .LBB0_568
	s_ashr_i32 s17, s16, 31
	v_lshl_add_u64 v[108:109], s[16:17], 0, v[32:33]
	v_lshl_add_u64 v[108:109], v[108:109], 2, s[14:15]
	s_waitcnt vmcnt(62)
	v_mul_f32_e32 v1, v1, v191
	s_nop 0
.LBB0_568:
	s_and_b64 vcc, exec, s[6:7]
	ds_write_b32 v73, v1 offset:264
	s_cbranch_vccnz .LBB0_570
	s_ashr_i32 s17, s16, 31
	v_lshl_add_u64 v[0:1], s[16:17], 0, v[32:33]
	v_lshl_add_u64 v[0:1], v[0:1], 2, s[14:15]
	s_waitcnt vmcnt(61)
	v_mul_f32_e32 v2, v2, v192
	s_nop 0
.LBB0_570:
	s_and_b64 vcc, exec, s[6:7]
	ds_write_b32 v73, v2 offset:528
	s_cbranch_vccnz .LBB0_572
	s_ashr_i32 s17, s16, 31
	v_lshl_add_u64 v[0:1], s[16:17], 0, v[32:33]
	v_lshl_add_u64 v[0:1], v[0:1], 2, s[14:15]
	s_waitcnt vmcnt(60)
	v_mul_f32_e32 v3, v3, v193
	s_nop 0
.LBB0_572:
	s_and_b64 vcc, exec, s[6:7]
	ds_write_b32 v73, v3 offset:792
	s_cbranch_vccnz .LBB0_574
	s_ashr_i32 s17, s16, 31
	v_lshl_add_u64 v[0:1], s[16:17], 0, v[32:33]
	v_lshl_add_u64 v[0:1], v[0:1], 2, s[14:15]
	s_waitcnt vmcnt(59)
	v_mul_f32_e32 v4, v4, v194
	s_nop 0
.LBB0_574:
	s_and_b64 vcc, exec, s[6:7]
	ds_write_b32 v73, v4 offset:1056
	s_cbranch_vccnz .LBB0_576
	s_ashr_i32 s17, s16, 31
	v_lshl_add_u64 v[0:1], s[16:17], 0, v[32:33]
	v_lshl_add_u64 v[0:1], v[0:1], 2, s[14:15]
	s_waitcnt vmcnt(58)
	v_mul_f32_e32 v5, v5, v195
	s_nop 0
.LBB0_576:
	s_and_b64 vcc, exec, s[6:7]
	ds_write_b32 v73, v5 offset:1320
	s_cbranch_vccnz .LBB0_578
	s_ashr_i32 s17, s16, 31
	v_lshl_add_u64 v[0:1], s[16:17], 0, v[32:33]
	v_lshl_add_u64 v[0:1], v[0:1], 2, s[14:15]
	s_waitcnt vmcnt(57)
	v_mul_f32_e32 v6, v6, v196
	s_nop 0
.LBB0_578:
	s_and_b64 vcc, exec, s[6:7]
	ds_write_b32 v73, v6 offset:1584
	s_cbranch_vccnz .LBB0_580
	s_ashr_i32 s17, s16, 31
	v_lshl_add_u64 v[0:1], s[16:17], 0, v[32:33]
	v_lshl_add_u64 v[0:1], v[0:1], 2, s[14:15]
	s_waitcnt vmcnt(56)
	v_mul_f32_e32 v7, v7, v197
	s_nop 0
.LBB0_580:
	s_and_b64 vcc, exec, s[6:7]
	ds_write_b32 v73, v7 offset:1848
	s_cbranch_vccnz .LBB0_582
	s_ashr_i32 s17, s16, 31
	v_lshl_add_u64 v[0:1], s[16:17], 0, v[32:33]
	v_lshl_add_u64 v[0:1], v[0:1], 2, s[14:15]
	s_waitcnt vmcnt(55)
	v_mul_f32_e32 v8, v8, v198
	s_nop 0
.LBB0_582:
	s_and_b64 vcc, exec, s[6:7]
	ds_write_b32 v73, v8 offset:2112
	s_cbranch_vccnz .LBB0_584
	s_ashr_i32 s17, s16, 31
	v_lshl_add_u64 v[0:1], s[16:17], 0, v[32:33]
	v_lshl_add_u64 v[0:1], v[0:1], 2, s[14:15]
	s_waitcnt vmcnt(54)
	v_mul_f32_e32 v9, v9, v199
	s_nop 0
.LBB0_584:
	s_and_b64 vcc, exec, s[6:7]
	ds_write_b32 v73, v9 offset:2376
	s_cbranch_vccnz .LBB0_586
	s_ashr_i32 s17, s16, 31
	v_lshl_add_u64 v[0:1], s[16:17], 0, v[32:33]
	v_lshl_add_u64 v[0:1], v[0:1], 2, s[14:15]
	s_waitcnt vmcnt(53)
	v_mul_f32_e32 v10, v10, v200
	s_nop 0
.LBB0_586:
	s_and_b64 vcc, exec, s[6:7]
	ds_write_b32 v73, v10 offset:2640
	s_cbranch_vccnz .LBB0_588
	s_ashr_i32 s17, s16, 31
	v_lshl_add_u64 v[0:1], s[16:17], 0, v[32:33]
	v_lshl_add_u64 v[0:1], v[0:1], 2, s[14:15]
	s_waitcnt vmcnt(52)
	v_mul_f32_e32 v11, v11, v201
	s_nop 0
.LBB0_588:
	s_and_b64 vcc, exec, s[6:7]
	ds_write_b32 v73, v11 offset:2904
	s_cbranch_vccnz .LBB0_590
	s_ashr_i32 s17, s16, 31
	v_lshl_add_u64 v[0:1], s[16:17], 0, v[32:33]
	v_lshl_add_u64 v[0:1], v[0:1], 2, s[14:15]
	s_waitcnt vmcnt(51)
	v_mul_f32_e32 v12, v12, v202
	s_nop 0
.LBB0_590:
	s_and_b64 vcc, exec, s[6:7]
	ds_write_b32 v73, v12 offset:3168
	s_cbranch_vccnz .LBB0_592
	s_ashr_i32 s17, s16, 31
	v_lshl_add_u64 v[0:1], s[16:17], 0, v[32:33]
	v_lshl_add_u64 v[0:1], v[0:1], 2, s[14:15]
	s_waitcnt vmcnt(50)
	v_mul_f32_e32 v13, v13, v203
	s_nop 0
.LBB0_592:
	s_and_b64 vcc, exec, s[6:7]
	ds_write_b32 v73, v13 offset:3432
	s_cbranch_vccnz .LBB0_594
	s_ashr_i32 s17, s16, 31
	v_lshl_add_u64 v[0:1], s[16:17], 0, v[32:33]
	v_lshl_add_u64 v[0:1], v[0:1], 2, s[14:15]
	s_waitcnt vmcnt(49)
	v_mul_f32_e32 v14, v14, v204
	s_nop 0
.LBB0_594:
	s_and_b64 vcc, exec, s[6:7]
	ds_write_b32 v73, v14 offset:3696
	s_cbranch_vccnz .LBB0_596
	s_ashr_i32 s17, s16, 31
	v_lshl_add_u64 v[0:1], s[16:17], 0, v[32:33]
	v_lshl_add_u64 v[0:1], v[0:1], 2, s[14:15]
	s_waitcnt vmcnt(48)
	v_mul_f32_e32 v15, v15, v205
	s_nop 0
; __device__ __forceinline__ void tr_store(const float (&v)[32], const TrDesc& d, LAS float* scr, int lane) {
;     ...
;     for (int i = 0; i < 32; ++i) { const int kk = 2 * i + (lane >> 5); float x = v[i]; if (d.gk) x *= d.gk[d.k0 + kk]; scr[kk * 33 + (lane & 31)] = x; }
; __global__ void __launch_bounds__(NWAVES * 64, 2) hybrid_fwd(Args args) {
;     ...
;                 for (; it < I_ALL; it += TSTEP) {
;                     { const int q = it + 2 * TSTEP < I_ALL ? it + 2 * TSTEP : it; TR_DECODE(q, d2); }
;                     tr_load(vc, d2, lane);
;                     tr_store(va, d0, scr, lane);
.LBB0_596:
	s_and_b64 vcc, exec, s[6:7]
	ds_write_b32 v73, v15 offset:3960
	s_cbranch_vccnz .LBB0_598
	s_ashr_i32 s17, s16, 31
	v_lshl_add_u64 v[0:1], s[16:17], 0, v[32:33]
	v_lshl_add_u64 v[0:1], v[0:1], 2, s[14:15]
	s_waitcnt vmcnt(47)
	v_mul_f32_e32 v16, v16, v206
	s_nop 0
.LBB0_598:
	s_and_b64 vcc, exec, s[6:7]
	ds_write_b32 v73, v16 offset:4224
	s_cbranch_vccnz .LBB0_600
	s_ashr_i32 s17, s16, 31
	v_lshl_add_u64 v[0:1], s[16:17], 0, v[32:33]
	v_lshl_add_u64 v[0:1], v[0:1], 2, s[14:15]
	s_waitcnt vmcnt(46)
	v_mul_f32_e32 v17, v17, v207
	s_nop 0
.LBB0_600:
	s_and_b64 vcc, exec, s[6:7]
	ds_write_b32 v73, v17 offset:4488
	s_cbranch_vccnz .LBB0_602
	s_ashr_i32 s17, s16, 31
	v_lshl_add_u64 v[0:1], s[16:17], 0, v[32:33]
	v_lshl_add_u64 v[0:1], v[0:1], 2, s[14:15]
	s_waitcnt vmcnt(45)
	v_mul_f32_e32 v18, v18, v208
	s_nop 0
.LBB0_602:
	s_and_b64 vcc, exec, s[6:7]
	ds_write_b32 v73, v18 offset:4752
	s_cbranch_vccnz .LBB0_604
	s_ashr_i32 s17, s16, 31
	v_lshl_add_u64 v[0:1], s[16:17], 0, v[32:33]
	v_lshl_add_u64 v[0:1], v[0:1], 2, s[14:15]
	s_waitcnt vmcnt(44)
	v_mul_f32_e32 v19, v19, v209
	s_nop 0
.LBB0_604:
	s_and_b64 vcc, exec, s[6:7]
	ds_write_b32 v73, v19 offset:5016
	s_cbranch_vccnz .LBB0_606
	s_ashr_i32 s17, s16, 31
	v_lshl_add_u64 v[0:1], s[16:17], 0, v[32:33]
	v_lshl_add_u64 v[0:1], v[0:1], 2, s[14:15]
	s_waitcnt vmcnt(43)
	v_mul_f32_e32 v20, v20, v210
	s_nop 0
.LBB0_606:
	s_and_b64 vcc, exec, s[6:7]
	ds_write_b32 v73, v20 offset:5280
	s_cbranch_vccnz .LBB0_608
	s_ashr_i32 s17, s16, 31
	v_lshl_add_u64 v[0:1], s[16:17], 0, v[32:33]
	v_lshl_add_u64 v[0:1], v[0:1], 2, s[14:15]
	s_waitcnt vmcnt(42)
	v_mul_f32_e32 v21, v21, v211
	s_nop 0
.LBB0_608:
	s_and_b64 vcc, exec, s[6:7]
	ds_write_b32 v73, v21 offset:5544
	s_cbranch_vccnz .LBB0_610
	s_ashr_i32 s17, s16, 31
	v_lshl_add_u64 v[0:1], s[16:17], 0, v[32:33]
	v_lshl_add_u64 v[0:1], v[0:1], 2, s[14:15]
	s_waitcnt vmcnt(41)
	v_mul_f32_e32 v22, v22, v212
	s_nop 0
.LBB0_610:
	s_and_b64 vcc, exec, s[6:7]
	ds_write_b32 v73, v22 offset:5808
	s_cbranch_vccnz .LBB0_612
	s_ashr_i32 s17, s16, 31
	v_lshl_add_u64 v[0:1], s[16:17], 0, v[32:33]
	v_lshl_add_u64 v[0:1], v[0:1], 2, s[14:15]
	s_waitcnt vmcnt(40)
	v_mul_f32_e32 v23, v23, v213
	s_nop 0
.LBB0_612:
	s_and_b64 vcc, exec, s[6:7]
	ds_write_b32 v73, v23 offset:6072
	s_cbranch_vccnz .LBB0_614
	s_ashr_i32 s17, s16, 31
	v_lshl_add_u64 v[0:1], s[16:17], 0, v[32:33]
	v_lshl_add_u64 v[0:1], v[0:1], 2, s[14:15]
	s_waitcnt vmcnt(39)
	v_mul_f32_e32 v24, v24, v214
	s_nop 0
.LBB0_614:
	s_and_b64 vcc, exec, s[6:7]
	ds_write_b32 v73, v24 offset:6336
	s_cbranch_vccnz .LBB0_616
	s_ashr_i32 s17, s16, 31
	v_lshl_add_u64 v[0:1], s[16:17], 0, v[32:33]
	v_lshl_add_u64 v[0:1], v[0:1], 2, s[14:15]
	s_waitcnt vmcnt(38)
	v_mul_f32_e32 v25, v25, v215
	s_nop 0
.LBB0_616:
	s_and_b64 vcc, exec, s[6:7]
	ds_write_b32 v73, v25 offset:6600
	s_cbranch_vccnz .LBB0_618
	s_ashr_i32 s17, s16, 31
	v_lshl_add_u64 v[0:1], s[16:17], 0, v[32:33]
	v_lshl_add_u64 v[0:1], v[0:1], 2, s[14:15]
	s_waitcnt vmcnt(37)
	v_mul_f32_e32 v26, v26, v216
	s_nop 0
.LBB0_618:
	s_and_b64 vcc, exec, s[6:7]
	ds_write_b32 v73, v26 offset:6864
	s_cbranch_vccnz .LBB0_620
	s_ashr_i32 s17, s16, 31
	v_lshl_add_u64 v[0:1], s[16:17], 0, v[32:33]
	v_lshl_add_u64 v[0:1], v[0:1], 2, s[14:15]
	s_waitcnt vmcnt(36)
	v_mul_f32_e32 v27, v27, v217
	s_nop 0
.LBB0_620:
	s_and_b64 vcc, exec, s[6:7]
	ds_write_b32 v73, v27 offset:7128
	s_cbranch_vccnz .LBB0_622
	s_ashr_i32 s17, s16, 31
	v_lshl_add_u64 v[0:1], s[16:17], 0, v[32:33]
	v_lshl_add_u64 v[0:1], v[0:1], 2, s[14:15]
	s_waitcnt vmcnt(35)
	v_mul_f32_e32 v28, v28, v218
	s_nop 0
.LBB0_622:
	s_and_b64 vcc, exec, s[6:7]
	ds_write_b32 v73, v28 offset:7392
	s_cbranch_vccnz .LBB0_624
	s_ashr_i32 s17, s16, 31
	v_lshl_add_u64 v[0:1], s[16:17], 0, v[32:33]
	v_lshl_add_u64 v[0:1], v[0:1], 2, s[14:15]
	s_waitcnt vmcnt(34)
	v_mul_f32_e32 v29, v29, v219
	s_nop 0
.LBB0_624:
	s_and_b64 vcc, exec, s[6:7]
	ds_write_b32 v73, v29 offset:7656
	s_cbranch_vccnz .LBB0_626
	s_ashr_i32 s17, s16, 31
	v_lshl_add_u64 v[0:1], s[16:17], 0, v[32:33]
	v_lshl_add_u64 v[0:1], v[0:1], 2, s[14:15]
	s_waitcnt vmcnt(33)
	v_mul_f32_e32 v30, v30, v220
	s_nop 0
.LBB0_626:
	s_and_b64 vcc, exec, s[86:87]
	ds_write_b32 v73, v30 offset:7920
	s_cbranch_vccz .LBB0_628
	s_ashr_i32 s17, s16, 31
	v_lshl_add_u64 v[0:1], s[16:17], 0, v[32:33]
	v_lshl_add_u64 v[0:1], v[0:1], 2, s[14:15]
	s_waitcnt vmcnt(32)
	v_mul_f32_e32 v0, v31, v221
	s_nop 0
	s_cbranch_execnz .LBB0_552
	s_branch .LBB0_629
